# v109 + grid barrier: XCD leaders wait on the TOP arrival counter reaching nx*(round+1) instead of on the separately bumped TOPGEN word
# speedup vs baseline: 1.0112x; 1.0001x over previous
.LBB0_169:
	s_or_b64 exec, exec, s[10:11]
	v_cvt_f32_u32_e32 v3, v0
	s_waitcnt vmcnt(0)
	v_readfirstlane_b32 s8, v2
	s_add_u32 s10, s40, 0x7500
	s_addc_u32 s11, s41, 0
	v_rcp_iflag_f32_e32 v3, v3
	v_add_u32_e32 v1, s8, v1
	v_add_u32_e32 v4, 1, v1
	s_mov_b64 s[20:21], -1
	v_mul_f32_e32 v2, 0x4f7ffffe, v3
	v_cvt_u32_f32_e32 v2, v2
	v_sub_u32_e32 v3, 0, v0
	v_mul_lo_u32 v3, v3, v2
	v_mul_hi_u32 v3, v2, v3
	v_add_u32_e32 v2, v2, v3
	v_mul_hi_u32 v2, v1, v2
	v_mul_lo_u32 v3, v2, v0
	v_sub_u32_e32 v1, v1, v3
	v_add_u32_e32 v5, 1, v2
	v_cmp_ge_u32_e32 vcc, v1, v0
	v_sub_u32_e32 v3, v1, v0
	s_nop 0
	v_cndmask_b32_e32 v2, v2, v5, vcc
	v_cndmask_b32_e32 v1, v1, v3, vcc
	v_add_u32_e32 v3, 1, v2
	v_cmp_ge_u32_e32 vcc, v1, v0
	s_nop 1
	v_cndmask_b32_e32 v2, v2, v3, vcc
	v_mul_lo_u32 v1, v0, v2
	v_add_u32_e32 v0, v1, v0
	v_cmp_ne_u32_e32 vcc, v4, v0
	v_readfirstlane_b32 s98, v0
	v_mov_b64_e32 v[0:1], s[10:11]
	s_and_saveexec_b64 s[8:9], vcc
	s_cbranch_execz .LBB0_181
	v_mov_b32_e32 v0, 0
	global_load_dword v1, v0, s[10:11] offset:-256 sc1
	s_mov_b64 s[24:25], 0
	s_waitcnt vmcnt(0)
	v_cmp_gt_u32_e32 vcc, s98, v1
	s_and_saveexec_b64 s[22:23], vcc
	s_cbranch_execz .LBB0_180
	s_add_u32 s20, s40, 0x4200
	s_addc_u32 s21, s41, 0
	s_mov_b32 s26, 1
	s_branch .LBB0_173

.LBB0_177:
	global_load_dword v1, v0, s[10:11] offset:-256 sc1
	s_add_i32 s26, s26, 1
	s_mov_b64 s[34:35], -1
	s_waitcnt vmcnt(0)
	v_cmp_le_u32_e32 vcc, s98, v1
	s_orn2_b64 s[38:39], vcc, exec
	s_branch .LBB0_172

.LBB0_378:
	s_or_b64 exec, exec, s[10:11]
	v_cvt_f32_u32_e32 v3, v0
	s_waitcnt vmcnt(0)
	v_readfirstlane_b32 s8, v2
	s_add_u32 s10, s40, 0x7500
	s_addc_u32 s11, s41, 0
	v_rcp_iflag_f32_e32 v3, v3
	v_add_u32_e32 v1, s8, v1
	v_add_u32_e32 v4, 1, v1
	s_mov_b64 s[14:15], -1
	v_mul_f32_e32 v2, 0x4f7ffffe, v3
	v_cvt_u32_f32_e32 v2, v2
	v_sub_u32_e32 v3, 0, v0
	v_mul_lo_u32 v3, v3, v2
	v_mul_hi_u32 v3, v2, v3
	v_add_u32_e32 v2, v2, v3
	v_mul_hi_u32 v2, v1, v2
	v_mul_lo_u32 v3, v2, v0
	v_sub_u32_e32 v1, v1, v3
	v_add_u32_e32 v5, 1, v2
	v_cmp_ge_u32_e32 vcc, v1, v0
	v_sub_u32_e32 v3, v1, v0
	s_nop 0
	v_cndmask_b32_e32 v2, v2, v5, vcc
	v_cndmask_b32_e32 v1, v1, v3, vcc
	v_add_u32_e32 v3, 1, v2
	v_cmp_ge_u32_e32 vcc, v1, v0
	s_nop 1
	v_cndmask_b32_e32 v2, v2, v3, vcc
	v_mul_lo_u32 v1, v0, v2
	v_add_u32_e32 v0, v1, v0
	v_cmp_ne_u32_e32 vcc, v4, v0
	v_readfirstlane_b32 s98, v0
	v_mov_b64_e32 v[0:1], s[10:11]
	s_and_saveexec_b64 s[8:9], vcc
	s_cbranch_execz .LBB0_390
	v_mov_b32_e32 v0, 0
	global_load_dword v1, v0, s[10:11] offset:-256 sc1
	s_mov_b64 s[18:19], 0
	s_waitcnt vmcnt(0)
	v_cmp_gt_u32_e32 vcc, s98, v1
	s_and_saveexec_b64 s[16:17], vcc
	s_cbranch_execz .LBB0_389
	s_add_u32 s14, s40, 0x4200
	s_addc_u32 s15, s41, 0
	s_mov_b32 s26, 1
	s_branch .LBB0_382

.LBB0_386:
	global_load_dword v1, v0, s[10:11] offset:-256 sc1
	s_add_i32 s26, s26, 1
	s_mov_b64 s[22:23], -1
	s_waitcnt vmcnt(0)
	v_cmp_le_u32_e32 vcc, s98, v1
	s_orn2_b64 s[34:35], vcc, exec
	s_branch .LBB0_381

.LBB0_656:
	s_or_b64 exec, exec, s[10:11]
	v_cvt_f32_u32_e32 v3, v0
	s_waitcnt vmcnt(0)
	v_readfirstlane_b32 s8, v2
	s_add_u32 s10, s40, 0x7500
	s_addc_u32 s11, s41, 0
	v_rcp_iflag_f32_e32 v3, v3
	v_add_u32_e32 v1, s8, v1
	v_add_u32_e32 v4, 1, v1
	s_mov_b64 s[12:13], -1
	v_mul_f32_e32 v2, 0x4f7ffffe, v3
	v_cvt_u32_f32_e32 v2, v2
	v_sub_u32_e32 v3, 0, v0
	v_mul_lo_u32 v3, v3, v2
	v_mul_hi_u32 v3, v2, v3
	v_add_u32_e32 v2, v2, v3
	v_mul_hi_u32 v2, v1, v2
	v_mul_lo_u32 v3, v2, v0
	v_sub_u32_e32 v1, v1, v3
	v_add_u32_e32 v5, 1, v2
	v_cmp_ge_u32_e32 vcc, v1, v0
	v_sub_u32_e32 v3, v1, v0
	s_nop 0
	v_cndmask_b32_e32 v2, v2, v5, vcc
	v_cndmask_b32_e32 v1, v1, v3, vcc
	v_add_u32_e32 v3, 1, v2
	v_cmp_ge_u32_e32 vcc, v1, v0
	s_nop 1
	v_cndmask_b32_e32 v2, v2, v3, vcc
	v_mul_lo_u32 v1, v0, v2
	v_add_u32_e32 v0, v1, v0
	v_cmp_ne_u32_e32 vcc, v4, v0
	v_readfirstlane_b32 s98, v0
	v_mov_b64_e32 v[0:1], s[10:11]
	s_and_saveexec_b64 s[8:9], vcc
	s_cbranch_execz .LBB0_668
	v_mov_b32_e32 v0, 0
	global_load_dword v1, v0, s[10:11] offset:-256 sc1
	s_mov_b64 s[18:19], 0
	s_waitcnt vmcnt(0)
	v_cmp_gt_u32_e32 vcc, s98, v1
	s_and_saveexec_b64 s[16:17], vcc
	s_cbranch_execz .LBB0_667
	s_add_u32 s12, s40, 0x4200
	s_addc_u32 s13, s41, 0
	s_mov_b32 s26, 1
	s_branch .LBB0_660

.LBB0_664:
	global_load_dword v1, v0, s[10:11] offset:-256 sc1
	s_add_i32 s26, s26, 1
	s_mov_b64 s[22:23], -1
	s_waitcnt vmcnt(0)
	v_cmp_le_u32_e32 vcc, s98, v1
	s_orn2_b64 s[28:29], vcc, exec
	s_branch .LBB0_659

.LBB0_764:
	s_or_b64 exec, exec, s[10:11]
	v_cvt_f32_u32_e32 v3, v0
	s_waitcnt vmcnt(0)
	v_readfirstlane_b32 s8, v2
	s_add_u32 s10, s40, 0x7500
	s_addc_u32 s11, s41, 0
	v_rcp_iflag_f32_e32 v3, v3
	v_add_u32_e32 v1, s8, v1
	v_add_u32_e32 v4, 1, v1
	s_mov_b64 s[12:13], -1
	v_mul_f32_e32 v2, 0x4f7ffffe, v3
	v_cvt_u32_f32_e32 v2, v2
	v_sub_u32_e32 v3, 0, v0
	v_mul_lo_u32 v3, v3, v2
	v_mul_hi_u32 v3, v2, v3
	v_add_u32_e32 v2, v2, v3
	v_mul_hi_u32 v2, v1, v2
	v_mul_lo_u32 v3, v2, v0
	v_sub_u32_e32 v1, v1, v3
	v_add_u32_e32 v5, 1, v2
	v_cmp_ge_u32_e32 vcc, v1, v0
	v_sub_u32_e32 v3, v1, v0
	s_nop 0
	v_cndmask_b32_e32 v2, v2, v5, vcc
	v_cndmask_b32_e32 v1, v1, v3, vcc
	v_add_u32_e32 v3, 1, v2
	v_cmp_ge_u32_e32 vcc, v1, v0
	s_nop 1
	v_cndmask_b32_e32 v2, v2, v3, vcc
	v_mul_lo_u32 v1, v0, v2
	v_add_u32_e32 v0, v1, v0
	v_cmp_ne_u32_e32 vcc, v4, v0
	v_readfirstlane_b32 s98, v0
	v_mov_b64_e32 v[0:1], s[10:11]
	s_and_saveexec_b64 s[8:9], vcc
	s_cbranch_execz .LBB0_776
	v_mov_b32_e32 v0, 0
	global_load_dword v1, v0, s[10:11] offset:-256 sc1
	s_mov_b64 s[16:17], 0
	s_waitcnt vmcnt(0)
	v_cmp_gt_u32_e32 vcc, s98, v1
	s_and_saveexec_b64 s[14:15], vcc
	s_cbranch_execz .LBB0_775
	s_add_u32 s12, s40, 0x4200
	s_addc_u32 s13, s41, 0
	s_mov_b32 s26, 1
	s_branch .LBB0_768

.LBB0_772:
	global_load_dword v1, v0, s[10:11] offset:-256 sc1
	s_add_i32 s26, s26, 1
	s_mov_b64 s[20:21], -1
	s_waitcnt vmcnt(0)
	v_cmp_le_u32_e32 vcc, s98, v1
	s_orn2_b64 s[24:25], vcc, exec
	s_branch .LBB0_767

.LBB0_903:
	s_or_b64 exec, exec, s[12:13]
	v_cvt_f32_u32_e32 v37, v32
	s_waitcnt vmcnt(0)
	v_readfirstlane_b32 s10, v36
	s_add_u32 s12, s40, 0x7500
	s_addc_u32 s13, s41, 0
	v_rcp_iflag_f32_e32 v37, v37
	v_add_u32_e32 v33, s10, v33
	v_add_u32_e32 v38, 1, v33
	s_mov_b64 s[14:15], -1
	v_mul_f32_e32 v36, 0x4f7ffffe, v37
	v_cvt_u32_f32_e32 v36, v36
	v_sub_u32_e32 v37, 0, v32
	v_mul_lo_u32 v37, v37, v36
	v_mul_hi_u32 v37, v36, v37
	v_add_u32_e32 v36, v36, v37
	v_mul_hi_u32 v36, v33, v36
	v_mul_lo_u32 v37, v36, v32
	v_sub_u32_e32 v33, v33, v37
	v_add_u32_e32 v39, 1, v36
	v_cmp_ge_u32_e32 vcc, v33, v32
	v_sub_u32_e32 v37, v33, v32
	s_nop 0
	v_cndmask_b32_e32 v36, v36, v39, vcc
	v_cndmask_b32_e32 v33, v33, v37, vcc
	v_add_u32_e32 v37, 1, v36
	v_cmp_ge_u32_e32 vcc, v33, v32
	s_nop 1
	v_cndmask_b32_e32 v36, v36, v37, vcc
	v_mul_lo_u32 v33, v32, v36
	v_add_u32_e32 v32, v33, v32
	v_cmp_ne_u32_e32 vcc, v38, v32
	v_readfirstlane_b32 s98, v32
	v_mov_b64_e32 v[32:33], s[12:13]
	s_and_saveexec_b64 s[10:11], vcc
	s_cbranch_execz .LBB0_915
	v_mov_b32_e32 v32, 0
	global_load_dword v33, v32, s[12:13] offset:-256 sc1
	s_mov_b64 s[18:19], 0
	s_waitcnt vmcnt(0)
	v_cmp_gt_u32_e32 vcc, s98, v33
	s_and_saveexec_b64 s[16:17], vcc
	s_cbranch_execz .LBB0_914
	s_add_u32 s14, s40, 0x4200
	s_addc_u32 s15, s41, 0
	s_mov_b32 s28, 1
	s_branch .LBB0_907

.LBB0_911:
	global_load_dword v33, v32, s[12:13] offset:-256 sc1
	s_add_i32 s28, s28, 1
	s_mov_b64 s[22:23], -1
	s_waitcnt vmcnt(0)
	v_cmp_le_u32_e32 vcc, s98, v33
	s_orn2_b64 s[26:27], vcc, exec
	s_branch .LBB0_906

.LBB0_989:
	s_or_b64 exec, exec, s[12:13]
	v_cvt_f32_u32_e32 v3, v0
	s_waitcnt vmcnt(0)
	v_readfirstlane_b32 s8, v2
	s_add_u32 s12, s40, 0x7500
	s_addc_u32 s13, s41, 0
	v_rcp_iflag_f32_e32 v3, v3
	v_add_u32_e32 v1, s8, v1
	v_add_u32_e32 v4, 1, v1
	s_mov_b64 s[14:15], -1
	v_mul_f32_e32 v2, 0x4f7ffffe, v3
	v_cvt_u32_f32_e32 v2, v2
	v_sub_u32_e32 v3, 0, v0
	v_mul_lo_u32 v3, v3, v2
	v_mul_hi_u32 v3, v2, v3
	v_add_u32_e32 v2, v2, v3
	v_mul_hi_u32 v2, v1, v2
	v_mul_lo_u32 v3, v2, v0
	v_sub_u32_e32 v1, v1, v3
	v_add_u32_e32 v5, 1, v2
	v_cmp_ge_u32_e32 vcc, v1, v0
	v_sub_u32_e32 v3, v1, v0
	s_nop 0
	v_cndmask_b32_e32 v2, v2, v5, vcc
	v_cndmask_b32_e32 v1, v1, v3, vcc
	v_add_u32_e32 v3, 1, v2
	v_cmp_ge_u32_e32 vcc, v1, v0
	s_nop 1
	v_cndmask_b32_e32 v2, v2, v3, vcc
	v_mul_lo_u32 v1, v0, v2
	v_add_u32_e32 v0, v1, v0
	v_cmp_ne_u32_e32 vcc, v4, v0
	v_readfirstlane_b32 s98, v0
	v_mov_b64_e32 v[0:1], s[12:13]
	s_and_saveexec_b64 s[8:9], vcc
	s_cbranch_execz .LBB0_1001
	v_mov_b32_e32 v0, 0
	global_load_dword v1, v0, s[12:13] offset:-256 sc1
	s_mov_b64 s[18:19], 0
	s_waitcnt vmcnt(0)
	v_cmp_gt_u32_e32 vcc, s98, v1
	s_and_saveexec_b64 s[16:17], vcc
	s_cbranch_execz .LBB0_1000
	s_add_u32 s14, s40, 0x4200
	s_addc_u32 s15, s41, 0
	s_mov_b32 s28, 1
	s_branch .LBB0_993

.LBB0_997:
	global_load_dword v1, v0, s[12:13] offset:-256 sc1
	s_add_i32 s28, s28, 1
	s_mov_b64 s[22:23], -1
	s_waitcnt vmcnt(0)
	v_cmp_le_u32_e32 vcc, s98, v1
	s_orn2_b64 s[26:27], vcc, exec
	s_branch .LBB0_992

.LBB0_1095:
	s_or_b64 exec, exec, s[14:15]
	v_cvt_f32_u32_e32 v3, v0
	s_waitcnt vmcnt(0)
	v_readfirstlane_b32 s12, v2
	s_add_u32 s14, s40, 0x7500
	s_addc_u32 s15, s41, 0
	v_rcp_iflag_f32_e32 v3, v3
	v_add_u32_e32 v1, s12, v1
	v_add_u32_e32 v4, 1, v1
	s_mov_b64 s[16:17], -1
	v_mul_f32_e32 v2, 0x4f7ffffe, v3
	v_cvt_u32_f32_e32 v2, v2
	v_sub_u32_e32 v3, 0, v0
	v_mul_lo_u32 v3, v3, v2
	v_mul_hi_u32 v3, v2, v3
	v_add_u32_e32 v2, v2, v3
	v_mul_hi_u32 v2, v1, v2
	v_mul_lo_u32 v3, v2, v0
	v_sub_u32_e32 v1, v1, v3
	v_add_u32_e32 v5, 1, v2
	v_cmp_ge_u32_e32 vcc, v1, v0
	v_sub_u32_e32 v3, v1, v0
	s_nop 0
	v_cndmask_b32_e32 v2, v2, v5, vcc
	v_cndmask_b32_e32 v1, v1, v3, vcc
	v_add_u32_e32 v3, 1, v2
	v_cmp_ge_u32_e32 vcc, v1, v0
	s_nop 1
	v_cndmask_b32_e32 v2, v2, v3, vcc
	v_mul_lo_u32 v1, v0, v2
	v_add_u32_e32 v0, v1, v0
	v_cmp_ne_u32_e32 vcc, v4, v0
	v_readfirstlane_b32 s98, v0
	v_mov_b64_e32 v[0:1], s[14:15]
	s_and_saveexec_b64 s[12:13], vcc
	s_cbranch_execz .LBB0_1107
	v_mov_b32_e32 v0, 0
	global_load_dword v1, v0, s[14:15] offset:-256 sc1
	s_mov_b64 s[22:23], 0
	s_waitcnt vmcnt(0)
	v_cmp_gt_u32_e32 vcc, s98, v1
	s_and_saveexec_b64 s[20:21], vcc
	s_cbranch_execz .LBB0_1106
	s_add_u32 s16, s40, 0x4200
	s_addc_u32 s17, s41, 0
	s_mov_b32 s34, 1
	s_branch .LBB0_1099

.LBB0_1103:
	global_load_dword v1, v0, s[14:15] offset:-256 sc1
	s_add_i32 s34, s34, 1
	s_mov_b64 s[26:27], -1
	s_waitcnt vmcnt(0)
	v_cmp_le_u32_e32 vcc, s98, v1
	s_orn2_b64 s[30:31], vcc, exec
	s_branch .LBB0_1098

.LBB0_1213:
	s_or_b64 exec, exec, s[10:11]
	v_cvt_f32_u32_e32 v3, v0
	s_waitcnt vmcnt(0)
	v_readfirstlane_b32 s8, v2
	s_add_u32 s10, s40, 0x7500
	s_addc_u32 s11, s41, 0
	v_rcp_iflag_f32_e32 v3, v3
	v_add_u32_e32 v1, s8, v1
	v_add_u32_e32 v4, 1, v1
	s_mov_b64 s[14:15], -1
	v_mul_f32_e32 v2, 0x4f7ffffe, v3
	v_cvt_u32_f32_e32 v2, v2
	v_sub_u32_e32 v3, 0, v0
	v_mul_lo_u32 v3, v3, v2
	v_mul_hi_u32 v3, v2, v3
	v_add_u32_e32 v2, v2, v3
	v_mul_hi_u32 v2, v1, v2
	v_mul_lo_u32 v3, v2, v0
	v_sub_u32_e32 v1, v1, v3
	v_add_u32_e32 v5, 1, v2
	v_cmp_ge_u32_e32 vcc, v1, v0
	v_sub_u32_e32 v3, v1, v0
	s_nop 0
	v_cndmask_b32_e32 v2, v2, v5, vcc
	v_cndmask_b32_e32 v1, v1, v3, vcc
	v_add_u32_e32 v3, 1, v2
	v_cmp_ge_u32_e32 vcc, v1, v0
	s_nop 1
	v_cndmask_b32_e32 v2, v2, v3, vcc
	v_mul_lo_u32 v1, v0, v2
	v_add_u32_e32 v0, v1, v0
	v_cmp_ne_u32_e32 vcc, v4, v0
	v_readfirstlane_b32 s98, v0
	v_mov_b64_e32 v[0:1], s[10:11]
	s_and_saveexec_b64 s[8:9], vcc
	s_cbranch_execz .LBB0_1225
	v_mov_b32_e32 v0, 0
	global_load_dword v1, v0, s[10:11] offset:-256 sc1
	s_mov_b64 s[20:21], 0
	s_waitcnt vmcnt(0)
	v_cmp_gt_u32_e32 vcc, s98, v1
	s_and_saveexec_b64 s[16:17], vcc
	s_cbranch_execz .LBB0_1224
	s_add_u32 s14, s40, 0x4200
	s_addc_u32 s15, s41, 0
	s_mov_b32 s30, 1
	s_branch .LBB0_1217

.LBB0_1221:
	global_load_dword v1, v0, s[10:11] offset:-256 sc1
	s_add_i32 s30, s30, 1
	s_mov_b64 s[24:25], -1
	s_waitcnt vmcnt(0)
	v_cmp_le_u32_e32 vcc, s98, v1
	s_orn2_b64 s[28:29], vcc, exec
	s_branch .LBB0_1216

.LBB0_1322:
	s_or_b64 exec, exec, s[10:11]
	v_cvt_f32_u32_e32 v3, v0
	s_waitcnt vmcnt(0)
	v_readfirstlane_b32 s3, v2
	s_add_u32 s10, s40, 0x7500
	s_addc_u32 s11, s41, 0
	v_rcp_iflag_f32_e32 v3, v3
	v_add_u32_e32 v1, s3, v1
	v_add_u32_e32 v4, 1, v1
	s_mov_b64 s[12:13], -1
	v_mul_f32_e32 v2, 0x4f7ffffe, v3
	v_cvt_u32_f32_e32 v2, v2
	v_sub_u32_e32 v3, 0, v0
	v_mul_lo_u32 v3, v3, v2
	v_mul_hi_u32 v3, v2, v3
	v_add_u32_e32 v2, v2, v3
	v_mul_hi_u32 v2, v1, v2
	v_mul_lo_u32 v3, v2, v0
	v_sub_u32_e32 v1, v1, v3
	v_add_u32_e32 v5, 1, v2
	v_cmp_ge_u32_e32 vcc, v1, v0
	v_sub_u32_e32 v3, v1, v0
	s_nop 0
	v_cndmask_b32_e32 v2, v2, v5, vcc
	v_cndmask_b32_e32 v1, v1, v3, vcc
	v_add_u32_e32 v3, 1, v2
	v_cmp_ge_u32_e32 vcc, v1, v0
	s_nop 1
	v_cndmask_b32_e32 v2, v2, v3, vcc
	v_mul_lo_u32 v1, v0, v2
	v_add_u32_e32 v0, v1, v0
	v_cmp_ne_u32_e32 vcc, v4, v0
	v_readfirstlane_b32 s98, v0
	v_mov_b64_e32 v[0:1], s[10:11]
	s_and_saveexec_b64 s[8:9], vcc
	s_cbranch_execz .LBB0_1334
	v_mov_b32_e32 v0, 0
	global_load_dword v1, v0, s[10:11] offset:-256 sc1
	s_mov_b64 s[16:17], 0
	s_waitcnt vmcnt(0)
	v_cmp_gt_u32_e32 vcc, s98, v1
	s_and_saveexec_b64 s[14:15], vcc
	s_cbranch_execz .LBB0_1333
	s_add_u32 s12, s40, 0x4200
	s_addc_u32 s13, s41, 0
	s_mov_b32 s3, 1
	s_branch .LBB0_1326

.LBB0_1330:
	global_load_dword v1, v0, s[10:11] offset:-256 sc1
	s_add_i32 s3, s3, 1
	s_mov_b64 s[22:23], -1
	s_waitcnt vmcnt(0)
	v_cmp_le_u32_e32 vcc, s98, v1
	s_orn2_b64 s[28:29], vcc, exec
	s_branch .LBB0_1325
